# p15 with the M1 transposed stores also issued one step later (spare quads v244-247 borrowed + v206-209)
# speedup vs baseline: 1.0016x; 1.0016x over previous
.Lalign_skip_2:
	v_add_f32_e32 v149, v149, v151
	v_lshlrev_b32_e32 v151, 16, v173
	v_and_b32_e32 v153, 0xffff0000, v173
	v_add_f32_e32 v151, v151, v153
	v_add_f32_e32 v149, v149, v151
	v_lshlrev_b32_e32 v151, 16, v174
	v_and_b32_e32 v153, 0xffff0000, v174
	v_add_f32_e32 v151, v151, v153
	v_lshlrev_b32_e32 v153, 16, v175
	v_and_b32_e32 v154, 0xffff0000, v175
	v_add_f32_e32 v153, v153, v154
	v_add_f32_e32 v151, v151, v153
	v_add_f32_e32 v149, v149, v151
	v_mov_b32_e32 v151, v149
	s_nop 1
	v_permlane16_swap_b32_e32 v149, v151
	v_add_f32_e32 v149, v149, v151
	ds_read_b128 v[172:175], v170 offset:9216
	v_mov_b32_e32 v151, v149
	s_nop 1
	v_permlane32_swap_b32_e32 v149, v151
	v_add_f32_e32 v149, v149, v151
	v_fmamk_f32 v149, v149, 0x3a000000, v240
	v_rsq_f32_e32 v154, v149
	s_waitcnt lgkmcnt(0)
	v_lshlrev_b32_e32 v149, 16, v172
	v_and_b32_e32 v151, 0xffff0000, v172
	v_add_f32_e32 v149, v149, v151
	v_lshlrev_b32_e32 v151, 16, v173
	v_and_b32_e32 v153, 0xffff0000, v173
	v_add_f32_e32 v151, v151, v153
	v_add_f32_e32 v149, v149, v151
	v_lshlrev_b32_e32 v151, 16, v174
	v_and_b32_e32 v153, 0xffff0000, v174
	v_add_f32_e32 v151, v151, v153
	v_lshlrev_b32_e32 v153, 16, v175
	v_and_b32_e32 v155, 0xffff0000, v175
	v_add_f32_e32 v153, v153, v155
	v_add_f32_e32 v151, v151, v153
	v_add_f32_e32 v149, v149, v151
	v_mov_b32_e32 v151, v149
	s_nop 1
	v_permlane16_swap_b32_e32 v149, v151
	v_add_f32_e32 v149, v149, v151
	ds_read_b128 v[172:175], v170 offset:10240
	v_mov_b32_e32 v151, v149
	s_nop 1
	v_permlane32_swap_b32_e32 v149, v151
	v_add_f32_e32 v149, v149, v151
	v_fmamk_f32 v149, v149, 0x3a000000, v240
	v_rsq_f32_e32 v160, v149
	s_waitcnt lgkmcnt(0)
	v_lshlrev_b32_e32 v149, 16, v172
	v_and_b32_e32 v151, 0xffff0000, v172
	v_add_f32_e32 v149, v149, v151
	v_lshlrev_b32_e32 v151, 16, v173
	v_and_b32_e32 v153, 0xffff0000, v173
	v_add_f32_e32 v151, v151, v153
	v_add_f32_e32 v149, v149, v151
	v_lshlrev_b32_e32 v151, 16, v174
	v_and_b32_e32 v153, 0xffff0000, v174
	v_add_f32_e32 v151, v151, v153
	v_lshlrev_b32_e32 v153, 16, v175
	v_and_b32_e32 v155, 0xffff0000, v175
	v_add_f32_e32 v153, v153, v155
	v_add_f32_e32 v151, v151, v153
	v_add_f32_e32 v149, v149, v151
	v_mov_b32_e32 v151, v149
	s_nop 1
	v_permlane16_swap_b32_e32 v149, v151
	v_add_f32_e32 v149, v149, v151
	ds_read_b128 v[172:175], v170 offset:11264
	v_mov_b32_e32 v151, v149
	s_nop 1
	v_permlane32_swap_b32_e32 v149, v151
	v_add_f32_e32 v149, v149, v151
	v_fmamk_f32 v149, v149, 0x3a000000, v240
	v_rsq_f32_e32 v158, v149
	s_waitcnt lgkmcnt(0)
	v_lshlrev_b32_e32 v149, 16, v172
	v_and_b32_e32 v151, 0xffff0000, v172
	v_add_f32_e32 v149, v149, v151
	v_lshlrev_b32_e32 v151, 16, v173
	v_and_b32_e32 v153, 0xffff0000, v173
	v_add_f32_e32 v151, v151, v153
	v_add_f32_e32 v149, v149, v151
	v_lshlrev_b32_e32 v151, 16, v174
	v_and_b32_e32 v153, 0xffff0000, v174
	v_add_f32_e32 v151, v151, v153
	v_lshlrev_b32_e32 v153, 16, v175
	v_and_b32_e32 v155, 0xffff0000, v175
	v_add_f32_e32 v153, v153, v155
	v_add_f32_e32 v151, v151, v153
	v_add_f32_e32 v149, v149, v151
	v_mov_b32_e32 v151, v149
	v_fmamk_f32 v0, v0, 0x3a000000, v240
	s_nop 0
	v_permlane16_swap_b32_e32 v149, v151
	v_rsq_f32_e32 v0, v0
	v_add_f32_e32 v149, v149, v151
	v_mov_b32_e32 v151, v149
	s_nop 1
	v_permlane32_swap_b32_e32 v149, v151
	v_add_f32_e32 v149, v149, v151
	v_fmamk_f32 v149, v149, 0x3a000000, v240
	v_pk_mul_f32 v[122:123], v[122:123], v[0:1] op_sel_hi:[1,0]
	v_rsq_f32_e32 v162, v149
	v_ashrrev_i32_e32 v149, 31, v148
	v_max_f32_e32 v122, 0, v122
	v_lshl_add_u64 v[172:173], v[164:165], 1, v[138:139]
	v_lshlrev_b64 v[164:165], 14, v[148:149]
	v_pk_mul_f32 v[124:125], v[124:125], v[0:1] op_sel_hi:[1,0]
	v_mul_f32_e32 v149, v122, v122
	v_max_f32_e32 v122, 0, v123
	v_pk_mul_f32 v[126:127], v[126:127], v[0:1] op_sel_hi:[1,0]
	v_mul_f32_e32 v151, v122, v122
	v_max_f32_e32 v122, 0, v124
	v_pk_mul_f32 v[114:115], v[114:115], v[0:1] op_sel_hi:[1,0]
	v_pk_mul_f32 v[128:129], v[128:129], v[0:1] op_sel_hi:[1,0]
	v_max_f32_e32 v126, 0, v126
	v_max_f32_e32 v127, 0, v127
	v_mul_f32_e32 v153, v122, v122
	v_max_f32_e32 v122, 0, v125
	v_pk_mul_f32 v[120:121], v[120:121], v[0:1] op_sel_hi:[1,0]
	v_pk_mul_f32 v[118:119], v[118:119], v[0:1] op_sel_hi:[1,0]
	v_max_f32_e32 v114, 0, v114
	v_lshl_add_u64 v[164:165], v[172:173], 0, v[164:165]
	v_mul_f32_e32 v126, v126, v126
	v_mul_f32_e32 v127, v127, v127
	v_max_f32_e32 v128, 0, v128
	v_max_f32_e32 v129, 0, v129
	v_mul_f32_e32 v125, v122, v122
	v_cvt_pk_bf16_f32 v122, v126, v127
	v_pk_mul_f32 v[116:117], v[116:117], v[0:1] op_sel_hi:[1,0]
	v_max_f32_e32 v0, 0, v118
	v_max_f32_e32 v118, 0, v119
	v_max_f32_e32 v119, 0, v120
	v_max_f32_e32 v120, 0, v121
	v_mul_f32_e32 v121, v114, v114
	v_max_f32_e32 v114, 0, v115
	v_mul_f32_e32 v128, v128, v128
	v_mul_f32_e32 v129, v129, v129
	v_cvt_pk_bf16_f32 v123, v128, v129
	v_cvt_pk_bf16_f32 v124, v149, v151
	v_cvt_pk_bf16_f32 v125, v153, v125
	ds_bpermute_b32 v244, v171, v122
	ds_bpermute_b32 v245, v171, v123
	ds_bpermute_b32 v246, v171, v124
	ds_bpermute_b32 v247, v171, v125
	v_pk_mul_f32 v[106:107], v[106:107], v[152:153] op_sel_hi:[1,0]
	v_mul_f32_e32 v0, v0, v0
	v_mul_f32_e32 v122, v114, v114
	v_max_f32_e32 v114, 0, v116
	v_mul_f32_e32 v123, v114, v114
	v_max_f32_e32 v114, 0, v117
	v_mul_f32_e32 v118, v118, v118
	v_mul_f32_e32 v117, v114, v114
	v_cvt_pk_bf16_f32 v114, v0, v118
	v_pk_mul_f32 v[112:113], v[112:113], v[152:153] op_sel_hi:[1,0]
	v_pk_mul_f32 v[110:111], v[110:111], v[152:153] op_sel_hi:[1,0]
	v_max_f32_e32 v106, 0, v106
	v_mul_f32_e32 v119, v119, v119
	v_mul_f32_e32 v120, v120, v120
	v_cvt_pk_bf16_f32 v115, v119, v120
	v_cvt_pk_bf16_f32 v116, v121, v122
	v_cvt_pk_bf16_f32 v117, v123, v117
	ds_bpermute_b32 v206, v171, v114
	ds_bpermute_b32 v207, v171, v115
	ds_bpermute_b32 v208, v171, v116
	ds_bpermute_b32 v209, v171, v117
	v_mov_b32_e32 v238, v164
	v_mov_b32_e32 v239, v165
	s_waitcnt lgkmcnt(4)
	global_store_dwordx4 v[238:239], v[244:247], off
	v_pk_mul_f32 v[108:109], v[108:109], v[152:153] op_sel_hi:[1,0]
	v_max_f32_e32 v0, 0, v110
	v_or_b32_e32 v114, 16, v148
	v_max_f32_e32 v110, 0, v111
	v_max_f32_e32 v111, 0, v112
	v_max_f32_e32 v112, 0, v113
	v_mul_f32_e32 v113, v106, v106
	v_max_f32_e32 v106, 0, v107
	v_ashrrev_i32_e32 v115, 31, v114
	v_mul_f32_e32 v116, v106, v106
	v_max_f32_e32 v106, 0, v108
	v_pk_mul_f32 v[98:99], v[98:99], v[152:153] op_sel_hi:[1,0]
	v_lshlrev_b64 v[114:115], 14, v[114:115]
	v_mul_f32_e32 v0, v0, v0
	v_mul_f32_e32 v117, v106, v106
	v_max_f32_e32 v106, 0, v109
	v_pk_mul_f32 v[104:105], v[104:105], v[152:153] op_sel_hi:[1,0]
	v_pk_mul_f32 v[102:103], v[102:103], v[152:153] op_sel_hi:[1,0]
	v_max_f32_e32 v98, 0, v98
	v_lshl_add_u64 v[114:115], v[172:173], 0, v[114:115]
	v_mul_f32_e32 v110, v110, v110
	v_mul_f32_e32 v109, v106, v106
	v_cvt_pk_bf16_f32 v106, v0, v110
	v_pk_mul_f32 v[100:101], v[100:101], v[152:153] op_sel_hi:[1,0]
	v_max_f32_e32 v0, 0, v102
	v_max_f32_e32 v102, 0, v103
	v_max_f32_e32 v103, 0, v104
	v_max_f32_e32 v104, 0, v105
	v_mul_f32_e32 v105, v98, v98
	v_max_f32_e32 v98, 0, v99
	v_mul_f32_e32 v111, v111, v111
	v_mul_f32_e32 v112, v112, v112
	v_cvt_pk_bf16_f32 v107, v111, v112
	v_cvt_pk_bf16_f32 v108, v113, v116
	v_cvt_pk_bf16_f32 v109, v117, v109
	s_waitcnt lgkmcnt(0)
	global_store_dwordx4 v[238:239], v[206:209], off offset:256
	ds_bpermute_b32 v244, v171, v106
	ds_bpermute_b32 v245, v171, v107
	ds_bpermute_b32 v246, v171, v108
	ds_bpermute_b32 v247, v171, v109
	v_pk_mul_f32 v[90:91], v[90:91], v[150:151] op_sel_hi:[1,0]
	v_mul_f32_e32 v0, v0, v0
	v_mul_f32_e32 v106, v98, v98
	v_max_f32_e32 v98, 0, v100
	v_mul_f32_e32 v107, v98, v98
	v_max_f32_e32 v98, 0, v101
	v_mul_f32_e32 v102, v102, v102
	v_mul_f32_e32 v101, v98, v98
	v_cvt_pk_bf16_f32 v98, v0, v102
	v_pk_mul_f32 v[96:97], v[96:97], v[150:151] op_sel_hi:[1,0]
	v_pk_mul_f32 v[94:95], v[94:95], v[150:151] op_sel_hi:[1,0]
	v_max_f32_e32 v90, 0, v90
	v_mul_f32_e32 v103, v103, v103
	v_mul_f32_e32 v104, v104, v104
	v_cvt_pk_bf16_f32 v99, v103, v104
	v_cvt_pk_bf16_f32 v100, v105, v106
	v_cvt_pk_bf16_f32 v101, v107, v101
	ds_bpermute_b32 v206, v171, v98
	ds_bpermute_b32 v207, v171, v99
	ds_bpermute_b32 v208, v171, v100
	ds_bpermute_b32 v209, v171, v101
	v_mov_b32_e32 v238, v114
	v_mov_b32_e32 v239, v115
	s_waitcnt lgkmcnt(4)
	global_store_dwordx4 v[238:239], v[244:247], off
	v_pk_mul_f32 v[92:93], v[92:93], v[150:151] op_sel_hi:[1,0]
	v_max_f32_e32 v0, 0, v94
	v_or_b32_e32 v98, 32, v148
	v_max_f32_e32 v94, 0, v95
	v_max_f32_e32 v95, 0, v96
	v_max_f32_e32 v96, 0, v97
	v_mul_f32_e32 v97, v90, v90
	v_max_f32_e32 v90, 0, v91
	v_ashrrev_i32_e32 v99, 31, v98
	v_mul_f32_e32 v100, v90, v90
	v_max_f32_e32 v90, 0, v92
	v_pk_mul_f32 v[82:83], v[82:83], v[150:151] op_sel_hi:[1,0]
	v_lshlrev_b64 v[98:99], 14, v[98:99]
	v_mul_f32_e32 v0, v0, v0
	v_mul_f32_e32 v101, v90, v90
	v_max_f32_e32 v90, 0, v93
	v_pk_mul_f32 v[88:89], v[88:89], v[150:151] op_sel_hi:[1,0]
	v_pk_mul_f32 v[86:87], v[86:87], v[150:151] op_sel_hi:[1,0]
	v_max_f32_e32 v82, 0, v82
	v_lshl_add_u64 v[98:99], v[172:173], 0, v[98:99]
	v_mul_f32_e32 v94, v94, v94
	v_mul_f32_e32 v93, v90, v90
	v_cvt_pk_bf16_f32 v90, v0, v94
	v_pk_mul_f32 v[84:85], v[84:85], v[150:151] op_sel_hi:[1,0]
	v_max_f32_e32 v0, 0, v86
	v_max_f32_e32 v86, 0, v87
	v_max_f32_e32 v87, 0, v88
	v_max_f32_e32 v88, 0, v89
	v_mul_f32_e32 v89, v82, v82
	v_max_f32_e32 v82, 0, v83
	v_mul_f32_e32 v95, v95, v95
	v_mul_f32_e32 v96, v96, v96
	v_cvt_pk_bf16_f32 v91, v95, v96
	v_cvt_pk_bf16_f32 v92, v97, v100
	v_cvt_pk_bf16_f32 v93, v101, v93
	s_waitcnt lgkmcnt(0)
	global_store_dwordx4 v[238:239], v[206:209], off offset:256
	ds_bpermute_b32 v244, v171, v90
	ds_bpermute_b32 v245, v171, v91
	ds_bpermute_b32 v246, v171, v92
	ds_bpermute_b32 v247, v171, v93
	v_pk_mul_f32 v[74:75], v[74:75], v[156:157] op_sel_hi:[1,0]
	v_mul_f32_e32 v0, v0, v0
	v_mul_f32_e32 v90, v82, v82
	v_max_f32_e32 v82, 0, v84
	v_mul_f32_e32 v91, v82, v82
	v_max_f32_e32 v82, 0, v85
	v_mul_f32_e32 v86, v86, v86
	v_mul_f32_e32 v85, v82, v82
	v_cvt_pk_bf16_f32 v82, v0, v86
	v_pk_mul_f32 v[80:81], v[80:81], v[156:157] op_sel_hi:[1,0]
	v_pk_mul_f32 v[78:79], v[78:79], v[156:157] op_sel_hi:[1,0]
	v_max_f32_e32 v74, 0, v74
	v_mul_f32_e32 v87, v87, v87
	v_mul_f32_e32 v88, v88, v88
	v_cvt_pk_bf16_f32 v83, v87, v88
	v_cvt_pk_bf16_f32 v84, v89, v90
	v_cvt_pk_bf16_f32 v85, v91, v85
	ds_bpermute_b32 v206, v171, v82
	ds_bpermute_b32 v207, v171, v83
	ds_bpermute_b32 v208, v171, v84
	ds_bpermute_b32 v209, v171, v85
	v_mov_b32_e32 v238, v98
	v_mov_b32_e32 v239, v99
	s_waitcnt lgkmcnt(4)
	global_store_dwordx4 v[238:239], v[244:247], off
	v_pk_mul_f32 v[76:77], v[76:77], v[156:157] op_sel_hi:[1,0]
	v_max_f32_e32 v0, 0, v78
	v_or_b32_e32 v82, 48, v148
	v_max_f32_e32 v78, 0, v79
	v_max_f32_e32 v79, 0, v80
	v_max_f32_e32 v80, 0, v81
	v_mul_f32_e32 v81, v74, v74
	v_max_f32_e32 v74, 0, v75
	v_ashrrev_i32_e32 v83, 31, v82
	v_mul_f32_e32 v84, v74, v74
	v_max_f32_e32 v74, 0, v76
	v_pk_mul_f32 v[66:67], v[66:67], v[156:157] op_sel_hi:[1,0]
	v_lshlrev_b64 v[82:83], 14, v[82:83]
	v_mul_f32_e32 v0, v0, v0
	v_mul_f32_e32 v85, v74, v74
	v_max_f32_e32 v74, 0, v77
	v_pk_mul_f32 v[72:73], v[72:73], v[156:157] op_sel_hi:[1,0]
	v_pk_mul_f32 v[70:71], v[70:71], v[156:157] op_sel_hi:[1,0]
	v_max_f32_e32 v66, 0, v66
	v_lshl_add_u64 v[82:83], v[172:173], 0, v[82:83]
	v_mul_f32_e32 v78, v78, v78
	v_mul_f32_e32 v77, v74, v74
	v_cvt_pk_bf16_f32 v74, v0, v78
	v_pk_mul_f32 v[68:69], v[68:69], v[156:157] op_sel_hi:[1,0]
	v_max_f32_e32 v0, 0, v70
	v_max_f32_e32 v70, 0, v71
	v_max_f32_e32 v71, 0, v72
	v_max_f32_e32 v72, 0, v73
	v_mul_f32_e32 v73, v66, v66
	v_max_f32_e32 v66, 0, v67
	v_mul_f32_e32 v79, v79, v79
	v_mul_f32_e32 v80, v80, v80
	v_cvt_pk_bf16_f32 v75, v79, v80
	v_cvt_pk_bf16_f32 v76, v81, v84
	v_cvt_pk_bf16_f32 v77, v85, v77
	s_waitcnt lgkmcnt(0)
	global_store_dwordx4 v[238:239], v[206:209], off offset:256
	ds_bpermute_b32 v244, v171, v74
	ds_bpermute_b32 v245, v171, v75
	ds_bpermute_b32 v246, v171, v76
	ds_bpermute_b32 v247, v171, v77
	v_pk_mul_f32 v[58:59], v[58:59], v[154:155] op_sel_hi:[1,0]
	v_mul_f32_e32 v0, v0, v0
	v_mul_f32_e32 v74, v66, v66
	v_max_f32_e32 v66, 0, v68
	v_mul_f32_e32 v75, v66, v66
	v_max_f32_e32 v66, 0, v69
	v_pk_mul_f32 v[64:65], v[64:65], v[154:155] op_sel_hi:[1,0]
	v_pk_mul_f32 v[62:63], v[62:63], v[154:155] op_sel_hi:[1,0]
	v_max_f32_e32 v58, 0, v58
	v_mul_f32_e32 v70, v70, v70
	v_mul_f32_e32 v71, v71, v71
	v_mul_f32_e32 v72, v72, v72
	v_mul_f32_e32 v69, v66, v66
	v_cvt_pk_bf16_f32 v66, v0, v70
	v_cvt_pk_bf16_f32 v67, v71, v72
	v_cvt_pk_bf16_f32 v68, v73, v74
	v_pk_mul_f32 v[60:61], v[60:61], v[154:155] op_sel_hi:[1,0]
	v_max_f32_e32 v0, 0, v62
	v_max_f32_e32 v62, 0, v63
	v_max_f32_e32 v63, 0, v64
	v_max_f32_e32 v64, 0, v65
	v_mul_f32_e32 v65, v58, v58
	v_max_f32_e32 v58, 0, v59
	v_cvt_pk_bf16_f32 v69, v75, v69
	ds_bpermute_b32 v206, v171, v66
	ds_bpermute_b32 v207, v171, v67
	ds_bpermute_b32 v208, v171, v68
	ds_bpermute_b32 v209, v171, v69
	v_mov_b32_e32 v238, v82
	v_mov_b32_e32 v239, v83
	s_waitcnt lgkmcnt(4)
	global_store_dwordx4 v[238:239], v[244:247], off
	v_mul_f32_e32 v62, v62, v62
	s_mov_b32 s7, 0x200000
	v_mul_f32_e32 v68, v58, v58
	v_max_f32_e32 v58, 0, v60
	v_mul_f32_e32 v69, v58, v58
	v_max_f32_e32 v58, 0, v61
	v_pk_mul_f32 v[50:51], v[50:51], v[154:155] op_sel_hi:[1,0]
	v_mul_f32_e32 v0, v0, v0
	v_mul_f32_e32 v63, v63, v63
	v_mul_f32_e32 v61, v58, v58
	v_cvt_pk_bf16_f32 v58, v0, v62
	v_add_co_u32_e32 v62, vcc, s7, v164
	v_pk_mul_f32 v[56:57], v[56:57], v[154:155] op_sel_hi:[1,0]
	v_pk_mul_f32 v[54:55], v[54:55], v[154:155] op_sel_hi:[1,0]
	v_max_f32_e32 v50, 0, v50
	v_mul_f32_e32 v64, v64, v64
	v_cvt_pk_bf16_f32 v59, v63, v64
	v_addc_co_u32_e32 v63, vcc, 0, v165, vcc
	v_pk_mul_f32 v[52:53], v[52:53], v[154:155] op_sel_hi:[1,0]
	v_max_f32_e32 v0, 0, v54
	v_max_f32_e32 v54, 0, v55
	v_max_f32_e32 v55, 0, v56
	v_max_f32_e32 v56, 0, v57
	v_mul_f32_e32 v57, v50, v50
	v_max_f32_e32 v50, 0, v51
	v_cvt_pk_bf16_f32 v60, v65, v68
	v_cvt_pk_bf16_f32 v61, v69, v61
	s_waitcnt lgkmcnt(0)
	global_store_dwordx4 v[238:239], v[206:209], off offset:256
	ds_bpermute_b32 v244, v171, v58
	ds_bpermute_b32 v245, v171, v59
	ds_bpermute_b32 v246, v171, v60
	ds_bpermute_b32 v247, v171, v61
	v_pk_mul_f32 v[42:43], v[42:43], v[160:161] op_sel_hi:[1,0]
	v_mul_f32_e32 v0, v0, v0
	v_mul_f32_e32 v58, v50, v50
	v_max_f32_e32 v50, 0, v52
	v_mul_f32_e32 v59, v50, v50
	v_max_f32_e32 v50, 0, v53
	v_pk_mul_f32 v[48:49], v[48:49], v[160:161] op_sel_hi:[1,0]
	v_pk_mul_f32 v[46:47], v[46:47], v[160:161] op_sel_hi:[1,0]
	v_max_f32_e32 v42, 0, v42
	v_lshl_add_u64 v[66:67], v[164:165], 0, s[50:51]
	v_mul_f32_e32 v54, v54, v54
	v_mul_f32_e32 v55, v55, v55
	v_mul_f32_e32 v56, v56, v56
	v_mul_f32_e32 v53, v50, v50
	v_cvt_pk_bf16_f32 v50, v0, v54
	v_cvt_pk_bf16_f32 v51, v55, v56
	v_cvt_pk_bf16_f32 v52, v57, v58
	v_pk_mul_f32 v[44:45], v[44:45], v[160:161] op_sel_hi:[1,0]
	v_max_f32_e32 v0, 0, v46
	v_max_f32_e32 v46, 0, v47
	v_max_f32_e32 v47, 0, v48
	v_max_f32_e32 v48, 0, v49
	v_mul_f32_e32 v49, v42, v42
	v_max_f32_e32 v42, 0, v43
	v_cvt_pk_bf16_f32 v53, v59, v53
	ds_bpermute_b32 v206, v171, v50
	ds_bpermute_b32 v207, v171, v51
	ds_bpermute_b32 v208, v171, v52
	ds_bpermute_b32 v209, v171, v53
	v_mov_b32_e32 v238, v66
	v_mov_b32_e32 v239, v67
	s_waitcnt lgkmcnt(4)
	global_store_dwordx4 v[238:239], v[244:247], off
	v_mul_f32_e32 v46, v46, v46
	s_mov_b32 s7, 0x240000
	v_mul_f32_e32 v52, v42, v42
	v_max_f32_e32 v42, 0, v44
	v_mul_f32_e32 v53, v42, v42
	v_max_f32_e32 v42, 0, v45
	v_pk_mul_f32 v[34:35], v[34:35], v[160:161] op_sel_hi:[1,0]
	v_mul_f32_e32 v0, v0, v0
	v_mul_f32_e32 v47, v47, v47
	v_mul_f32_e32 v45, v42, v42
	v_cvt_pk_bf16_f32 v42, v0, v46
	v_add_co_u32_e32 v46, vcc, s7, v164
	v_pk_mul_f32 v[40:41], v[40:41], v[160:161] op_sel_hi:[1,0]
	v_pk_mul_f32 v[38:39], v[38:39], v[160:161] op_sel_hi:[1,0]
	v_max_f32_e32 v34, 0, v34
	v_mul_f32_e32 v48, v48, v48
	v_cvt_pk_bf16_f32 v43, v47, v48
	v_addc_co_u32_e32 v47, vcc, 0, v165, vcc
	v_pk_mul_f32 v[36:37], v[36:37], v[160:161] op_sel_hi:[1,0]
	v_max_f32_e32 v0, 0, v38
	v_max_f32_e32 v38, 0, v39
	v_max_f32_e32 v39, 0, v40
	v_max_f32_e32 v40, 0, v41
	v_mul_f32_e32 v41, v34, v34
	v_max_f32_e32 v34, 0, v35
	v_cvt_pk_bf16_f32 v44, v49, v52
	v_cvt_pk_bf16_f32 v45, v53, v45
	s_waitcnt lgkmcnt(0)
	global_store_dwordx4 v[238:239], v[206:209], off offset:256
	ds_bpermute_b32 v244, v171, v42
	ds_bpermute_b32 v245, v171, v43
	ds_bpermute_b32 v246, v171, v44
	ds_bpermute_b32 v247, v171, v45
	v_pk_mul_f32 v[26:27], v[26:27], v[158:159] op_sel_hi:[1,0]
	s_mov_b64 s[10:11], 0x240000
	v_mul_f32_e32 v42, v34, v34
	v_max_f32_e32 v34, 0, v36
	v_mul_f32_e32 v0, v0, v0
	v_mul_f32_e32 v43, v34, v34
	v_max_f32_e32 v34, 0, v37
	v_pk_mul_f32 v[32:33], v[32:33], v[158:159] op_sel_hi:[1,0]
	v_pk_mul_f32 v[30:31], v[30:31], v[158:159] op_sel_hi:[1,0]
	v_max_f32_e32 v26, 0, v26
	v_lshl_add_u64 v[50:51], v[164:165], 0, s[10:11]
	v_mul_f32_e32 v38, v38, v38
	v_mul_f32_e32 v39, v39, v39
	v_mul_f32_e32 v40, v40, v40
	v_mul_f32_e32 v37, v34, v34
	v_cvt_pk_bf16_f32 v34, v0, v38
	v_cvt_pk_bf16_f32 v35, v39, v40
	v_cvt_pk_bf16_f32 v36, v41, v42
	v_pk_mul_f32 v[28:29], v[28:29], v[158:159] op_sel_hi:[1,0]
	v_max_f32_e32 v0, 0, v30
	v_max_f32_e32 v30, 0, v31
	v_max_f32_e32 v31, 0, v32
	v_max_f32_e32 v32, 0, v33
	v_mul_f32_e32 v33, v26, v26
	v_max_f32_e32 v26, 0, v27
	v_cvt_pk_bf16_f32 v37, v43, v37
	ds_bpermute_b32 v206, v171, v34
	ds_bpermute_b32 v207, v171, v35
	ds_bpermute_b32 v208, v171, v36
	ds_bpermute_b32 v209, v171, v37
	v_mov_b32_e32 v238, v50
	v_mov_b32_e32 v239, v51
	s_waitcnt lgkmcnt(4)
	global_store_dwordx4 v[238:239], v[244:247], off
	v_mul_f32_e32 v30, v30, v30
	s_mov_b32 s7, 0x280000
	v_mul_f32_e32 v36, v26, v26
	v_max_f32_e32 v26, 0, v28
	v_mul_f32_e32 v37, v26, v26
	v_max_f32_e32 v26, 0, v29
	v_pk_mul_f32 v[18:19], v[18:19], v[158:159] op_sel_hi:[1,0]
	v_mul_f32_e32 v0, v0, v0
	v_mul_f32_e32 v31, v31, v31
	v_mul_f32_e32 v29, v26, v26
	v_cvt_pk_bf16_f32 v26, v0, v30
	v_add_co_u32_e32 v30, vcc, s7, v164
	v_pk_mul_f32 v[24:25], v[24:25], v[158:159] op_sel_hi:[1,0]
	v_pk_mul_f32 v[22:23], v[22:23], v[158:159] op_sel_hi:[1,0]
	v_max_f32_e32 v18, 0, v18
	v_mul_f32_e32 v32, v32, v32
	v_cvt_pk_bf16_f32 v27, v31, v32
	v_addc_co_u32_e32 v31, vcc, 0, v165, vcc
	v_pk_mul_f32 v[20:21], v[20:21], v[158:159] op_sel_hi:[1,0]
	v_max_f32_e32 v0, 0, v22
	v_max_f32_e32 v22, 0, v23
	v_max_f32_e32 v23, 0, v24
	v_max_f32_e32 v24, 0, v25
	v_mul_f32_e32 v25, v18, v18
	v_max_f32_e32 v18, 0, v19
	v_cvt_pk_bf16_f32 v28, v33, v36
	v_cvt_pk_bf16_f32 v29, v37, v29
	s_waitcnt lgkmcnt(0)
	global_store_dwordx4 v[238:239], v[206:209], off offset:256
	ds_bpermute_b32 v244, v171, v26
	ds_bpermute_b32 v245, v171, v27
	ds_bpermute_b32 v246, v171, v28
	ds_bpermute_b32 v247, v171, v29
	v_pk_mul_f32 v[10:11], v[10:11], v[162:163] op_sel_hi:[1,0]
	s_mov_b64 s[10:11], 0x280000
	v_mul_f32_e32 v26, v18, v18
	v_max_f32_e32 v18, 0, v20
	v_mul_f32_e32 v0, v0, v0
	v_mul_f32_e32 v27, v18, v18
	v_max_f32_e32 v18, 0, v21
	v_pk_mul_f32 v[16:17], v[16:17], v[162:163] op_sel_hi:[1,0]
	v_pk_mul_f32 v[14:15], v[14:15], v[162:163] op_sel_hi:[1,0]
	v_max_f32_e32 v10, 0, v10
	v_lshl_add_u64 v[34:35], v[164:165], 0, s[10:11]
	v_mul_f32_e32 v22, v22, v22
	v_mul_f32_e32 v23, v23, v23
	v_mul_f32_e32 v24, v24, v24
	v_mul_f32_e32 v21, v18, v18
	v_cvt_pk_bf16_f32 v18, v0, v22
	v_cvt_pk_bf16_f32 v19, v23, v24
	v_cvt_pk_bf16_f32 v20, v25, v26
	v_pk_mul_f32 v[12:13], v[12:13], v[162:163] op_sel_hi:[1,0]
	v_max_f32_e32 v0, 0, v14
	v_max_f32_e32 v14, 0, v15
	v_max_f32_e32 v15, 0, v16
	v_max_f32_e32 v16, 0, v17
	v_mul_f32_e32 v17, v10, v10
	v_max_f32_e32 v10, 0, v11
	v_cvt_pk_bf16_f32 v21, v27, v21
	ds_bpermute_b32 v206, v171, v18
	ds_bpermute_b32 v207, v171, v19
	ds_bpermute_b32 v208, v171, v20
	ds_bpermute_b32 v209, v171, v21
	v_mov_b32_e32 v238, v34
	v_mov_b32_e32 v239, v35
	s_waitcnt lgkmcnt(4)
	global_store_dwordx4 v[238:239], v[244:247], off
	v_mul_f32_e32 v0, v0, v0
	v_mul_f32_e32 v14, v14, v14
	v_mul_f32_e32 v20, v10, v10
	v_max_f32_e32 v10, 0, v12
	v_mul_f32_e32 v21, v10, v10
	v_max_f32_e32 v10, 0, v13
	s_mov_b32 s7, 0x2c0000
	v_pk_mul_f32 v[4:5], v[4:5], v[162:163] op_sel_hi:[1,0]
	v_pk_mul_f32 v[2:3], v[2:3], v[162:163] op_sel_hi:[1,0]
	v_pk_mul_f32 v[6:7], v[6:7], v[162:163] op_sel_hi:[1,0]
	v_mul_f32_e32 v15, v15, v15
	v_mul_f32_e32 v13, v10, v10
	v_cvt_pk_bf16_f32 v10, v0, v14
	v_add_co_u32_e32 v14, vcc, s7, v164
	v_pk_mul_f32 v[8:9], v[8:9], v[162:163] op_sel_hi:[1,0]
	v_max_f32_e32 v0, 0, v2
	v_max_f32_e32 v2, 0, v3
	v_max_f32_e32 v3, 0, v4
	v_max_f32_e32 v4, 0, v5
	v_max_f32_e32 v5, 0, v6
	s_mov_b64 s[10:11], 0x2c0000
	v_mul_f32_e32 v16, v16, v16
	v_cvt_pk_bf16_f32 v11, v15, v16
	v_addc_co_u32_e32 v15, vcc, 0, v165, vcc
	v_mul_f32_e32 v2, v2, v2
	v_mul_f32_e32 v3, v3, v3
	v_mul_f32_e32 v4, v4, v4
	v_mul_f32_e32 v5, v5, v5
	v_max_f32_e32 v6, 0, v7
	v_max_f32_e32 v7, 0, v8
	v_max_f32_e32 v8, 0, v9
	v_lshl_add_u64 v[18:19], v[164:165], 0, s[10:11]
	v_cvt_pk_bf16_f32 v12, v17, v20
	v_cvt_pk_bf16_f32 v13, v21, v13
	s_waitcnt lgkmcnt(0)
	global_store_dwordx4 v[238:239], v[206:209], off offset:256
	ds_bpermute_b32 v244, v171, v10
	ds_bpermute_b32 v245, v171, v11
	ds_bpermute_b32 v246, v171, v12
	ds_bpermute_b32 v247, v171, v13
	v_mul_f32_e32 v0, v0, v0
	v_mul_f32_e32 v6, v6, v6
	v_mul_f32_e32 v7, v7, v7
	v_mul_f32_e32 v8, v8, v8
	v_cvt_pk_bf16_f32 v2, v0, v2
	v_cvt_pk_bf16_f32 v3, v3, v4
	v_cvt_pk_bf16_f32 v4, v5, v6
	v_cvt_pk_bf16_f32 v5, v7, v8
	s_mov_b64 s[10:11], -1
	s_andn2_b64 vcc, exec, s[4:5]
	ds_bpermute_b32 v206, v171, v2
	ds_bpermute_b32 v207, v171, v3
	ds_bpermute_b32 v208, v171, v4
	ds_bpermute_b32 v209, v171, v5
	v_mov_b32_e32 v238, v18
	v_mov_b32_e32 v239, v19
	s_waitcnt lgkmcnt(4)
	global_store_dwordx4 v[238:239], v[244:247], off
	s_waitcnt lgkmcnt(0)
	global_store_dwordx4 v[238:239], v[206:209], off offset:256
	s_cbranch_vccnz .LBB0_1160
	s_andn2_b64 vcc, exec, s[0:1]
	s_cbranch_vccnz .LBB0_1159
	s_barrier
	s_branch .LBB0_1159

.LBB0_1218:
	s_or_b64 exec, exec, s[0:1]
	s_waitcnt lgkmcnt(0)
	s_barrier
	v_mov_b32_e32 v244, 0xbab64f3b
	v_not_b32_e32 v245, 31
	v_mov_b32_e32 v246, 0x7fc00000
	v_mov_b32_e32 v247, 0x7f800000
.LBB0_1219:
	v_readlane_b32 s2, v254, 2
	v_readlane_b32 s3, v254, 3
	s_cmp_ge_i32 s20, s2
	s_cselect_b64 s[0:1], -1, 0
	s_cmp_lt_i32 s20, s3
	s_cselect_b64 s[2:3], -1, 0
	s_and_b64 s[2:3], s[0:1], s[2:3]
	s_mov_b64 s[0:1], -1
	s_and_b64 vcc, exec, s[2:3]
	s_cbranch_vccnz .LBB0_1221
	s_add_i32 s0, s41, 2
	v_writelane_b32 v254, s0, 10
	s_mov_b64 s[0:1], 0
